# P1/P3/P9 K-loops: in the two six-load super-phases the last two LDS-DMA loads are issued inside the following MFMA block instead of the load segment (segment wait vmcnt(8)->6); on top of v64
# speedup vs baseline: 1.0032x; 1.0032x over previous
; #define PG8_STAGE(bufoff, gbase, voff) do { _Pragma("unroll") for (int _i = 0; _i < 2; ++_i) \
;         __builtin_amdgcn_global_load_lds((const unsigned*)((const char*)(gbase) + (voff)[_i]), (PG8_LAS unsigned*)(lds + (bufoff) + ldsw + _i * 8192), 16, 0, 0); } while (0)
; #define PG8_LDA(dst, b, h) do { _Pragma("unroll") for (int m = 0; m < 4; ++m) _Pragma("unroll") for (int k = 0; k < 2; ++k) dst[m][k] = *(const PG8_LAS bf16x8*)(lds + PG8_SA(b, h) + aoff + m * 2048 + k * 1024); } while (0)
; #define PG8_LDB(dst, b, h) do { _Pragma("unroll") for (int n = 0; n < 2; ++n) _Pragma("unroll") for (int k = 0; k < 2; ++k) dst[n][k] = *(const PG8_LAS bf16x8*)(lds + PG8_SB(b, h) + boff + n * 2048 + k * 1024); } while (0)
; #define PG8_MMA(ai, bj, At, Bt) do { __builtin_amdgcn_s_setprio(1); _Pragma("unroll") for (int m = 0; m < 4; ++m) _Pragma("unroll") for (int n = 0; n < 2; ++n) _Pragma("unroll") for (int k = 0; k < 2; ++k) \
;         acc[ai][bj][m][n] = __builtin_amdgcn_mfma_f32_16x16x32_bf16(Bt[n][k], At[m][k], acc[ai][bj][m][n], 0, 0, 0); __builtin_amdgcn_s_setprio(0); } while (0)
; #define PG8_WAIT_V(n) asm volatile("s_waitcnt vmcnt(" #n ")" ::: "memory")
; #define PG8_WAIT_L(n) asm volatile("s_waitcnt lgkmcnt(" #n ")" ::: "memory")
; #define PG8_BAR __builtin_amdgcn_s_barrier()
; #define PG8_SCHED __builtin_amdgcn_sched_barrier(0)
; template <class Epi, bool ALIGN_EPI, bool ABLK = false>
; __device__ __forceinline__ void gemm_phase(PG8_LAS unsigned char* lds, const Gemm g, const StaticOrder& S, const Epi& E) {
;     ...
;             const char* a1 = cA + (size_t)(t + 1) * kstepA;
;             const char* a2 = last ? nA : cA + (size_t)(t + 2) * kstepA; const char* b2 = last ? nB : cB + (size_t)(t + 2) * kstepB;
;             const char* a3 = a2 + kstepA; const char* b3 = b2 + kstepB;
;             PG8_LDB(B0, 0, 0); PG8_LDB(B1, 0, 1); PG8_SCHED; PG8_LDA(At, 0, 0); PG8_STAGE(PG8_SA(1, 1), a1 + hstepA, voffA);
;             PG8_WAIT_V(8); PG8_WAIT_L(0); PG8_BAR; PG8_MMA(0, 0, At, B0); PG8_MMA(0, 1, At, B1); PG8_BAR; PG8_SCHED;
;             PG8_LDA(At, 0, 1); PG8_STAGE(PG8_SB(0, 0), b2, voffB); PG8_STAGE(PG8_SB(0, 1), b2 + hstepB, voffB); PG8_STAGE(PG8_SA(0, 0), a2, voffA);
;             PG8_WAIT_V(8); PG8_WAIT_L(0); PG8_BAR; PG8_MMA(1, 0, At, B0); PG8_MMA(1, 1, At, B1); PG8_BAR; PG8_SCHED;
.LBB0_402:
	ds_read_b128 v[132:135], v251
	ds_read_b128 v[136:139], v251 offset:1024
	ds_read_b128 v[140:143], v251 offset:2048
	ds_read_b128 v[186:189], v251 offset:3072
	ds_read_b128 v[190:193], v251 offset:16384
	ds_read_b128 v[194:197], v251 offset:17408
	ds_read_b128 v[198:201], v251 offset:18432
	ds_read_b128 v[202:205], v251 offset:19456
	s_add_u32 s48, s24, s46
	s_addc_u32 s49, s25, s47
	s_cmp_eq_u32 s70, 12
	s_cselect_b32 s85, s41, s49
	s_cselect_b32 s84, s66, s48
	s_cselect_b32 s49, s39, s69
	s_cselect_b32 s48, s67, s68
	s_mov_b64 s[74:75], 0xc000
	s_add_i32 m0, s55, 0xc000
	s_mov_b64 s[74:75], 0xe000
	ds_read_b128 v[206:209], v183
	ds_read_b128 v[210:213], v183 offset:1024
	ds_read_b128 v[214:217], v183 offset:2048
	ds_read_b128 v[218:221], v183 offset:3072
	ds_read_b128 v[222:225], v183 offset:4096
	ds_read_b128 v[226:229], v183 offset:5120
	ds_read_b128 v[230:233], v183 offset:6144
	ds_read_b128 v[234:237], v183 offset:7168
	global_load_lds_dwordx4 v249, s[82:83]
	s_add_i32 m0, s55, 0xe000
	s_nop 0
	global_load_lds_dwordx4 v250, s[82:83]
	s_waitcnt vmcnt(8)
	s_waitcnt lgkmcnt(0)
	s_barrier
	s_setprio 1
	s_waitcnt lgkmcnt(0)
	v_mfma_f32_16x16x32_bf16 v[126:129], v[132:135], v[206:209], v[126:129]
	v_mfma_f32_16x16x32_bf16 v[122:125], v[140:143], v[206:209], v[122:125]
	v_mfma_f32_16x16x32_bf16 v[118:121], v[132:135], v[214:217], v[118:121]
	v_mfma_f32_16x16x32_bf16 v[114:117], v[140:143], v[214:217], v[114:117]
	v_mfma_f32_16x16x32_bf16 v[110:113], v[132:135], v[222:225], v[110:113]
	v_mfma_f32_16x16x32_bf16 v[106:109], v[140:143], v[222:225], v[106:109]
	v_mfma_f32_16x16x32_bf16 v[102:105], v[132:135], v[230:233], v[102:105]
	v_mfma_f32_16x16x32_bf16 v[98:101], v[140:143], v[230:233], v[98:101]
	v_mfma_f32_16x16x32_bf16 v[126:129], v[136:139], v[210:213], v[126:129]
	v_mfma_f32_16x16x32_bf16 v[122:125], v[186:189], v[210:213], v[122:125]
	v_mfma_f32_16x16x32_bf16 v[118:121], v[136:139], v[218:221], v[118:121]
	v_mfma_f32_16x16x32_bf16 v[114:117], v[186:189], v[218:221], v[114:117]
	v_mfma_f32_16x16x32_bf16 v[110:113], v[136:139], v[226:229], v[110:113]
	v_mfma_f32_16x16x32_bf16 v[106:109], v[186:189], v[226:229], v[106:109]
	v_mfma_f32_16x16x32_bf16 v[102:105], v[136:139], v[234:237], v[102:105]
	v_mfma_f32_16x16x32_bf16 v[98:101], v[186:189], v[234:237], v[98:101]
	s_setprio 0
	s_setprio 1
	v_mfma_f32_16x16x32_bf16 v[94:97], v[190:193], v[206:209], v[94:97]
	s_add_i32 s71, s64, s9
	v_mfma_f32_16x16x32_bf16 v[90:93], v[198:201], v[206:209], v[90:93]
	s_mov_b32 m0, s71
	v_mfma_f32_16x16x32_bf16 v[86:89], v[190:193], v[214:217], v[86:89]
	v_mfma_f32_16x16x32_bf16 v[82:85], v[198:201], v[214:217], v[82:85]
	v_mfma_f32_16x16x32_bf16 v[78:81], v[190:193], v[222:225], v[78:81]
	v_mfma_f32_16x16x32_bf16 v[74:77], v[198:201], v[222:225], v[74:77]
	v_mfma_f32_16x16x32_bf16 v[70:73], v[190:193], v[230:233], v[70:73]
	v_mfma_f32_16x16x32_bf16 v[66:69], v[198:201], v[230:233], v[66:69]
	v_mfma_f32_16x16x32_bf16 v[94:97], v[194:197], v[210:213], v[94:97]
	v_mfma_f32_16x16x32_bf16 v[90:93], v[202:205], v[210:213], v[90:93]
	v_mfma_f32_16x16x32_bf16 v[86:89], v[194:197], v[218:221], v[86:89]
	v_mfma_f32_16x16x32_bf16 v[82:85], v[202:205], v[218:221], v[82:85]
	v_mfma_f32_16x16x32_bf16 v[78:81], v[194:197], v[226:229], v[78:81]
	v_mfma_f32_16x16x32_bf16 v[74:77], v[202:205], v[226:229], v[74:77]
	v_mfma_f32_16x16x32_bf16 v[70:73], v[194:197], v[234:237], v[70:73]
	v_mfma_f32_16x16x32_bf16 v[66:69], v[202:205], v[234:237], v[66:69]
	s_setprio 0
	s_barrier
	ds_read_b128 v[206:209], v183 offset:16384
	ds_read_b128 v[210:213], v183 offset:17408
	ds_read_b128 v[214:217], v183 offset:18432
	ds_read_b128 v[218:221], v183 offset:19456
	ds_read_b128 v[222:225], v183 offset:20480
	ds_read_b128 v[226:229], v183 offset:21504
	ds_read_b128 v[230:233], v183 offset:22528
	ds_read_b128 v[234:237], v183 offset:23552
	global_load_lds_dwordx4 v148, s[48:49]
	s_add_i32 m0, s71, 0x2000
	s_add_u32 s74, s48, 0x40000
	s_addc_u32 s75, s49, 0
	s_add_i32 s71, s65, s9
	global_load_lds_dwordx4 v150, s[48:49]
	s_mov_b32 m0, s71
	s_nop 0
	global_load_lds_dwordx4 v148, s[74:75]
	s_add_i32 m0, s71, 0x2000
	s_nop 0
	global_load_lds_dwordx4 v150, s[74:75]
	s_waitcnt vmcnt(6)
	s_waitcnt lgkmcnt(0)
	s_barrier
	s_setprio 1
	s_waitcnt lgkmcnt(0)
	v_mfma_f32_16x16x32_bf16 v[62:65], v[132:135], v[206:209], v[62:65]
	v_mfma_f32_16x16x32_bf16 v[58:61], v[140:143], v[206:209], v[58:61]
	v_mfma_f32_16x16x32_bf16 v[54:57], v[132:135], v[214:217], v[54:57]
	v_mfma_f32_16x16x32_bf16 v[50:53], v[140:143], v[214:217], v[50:53]
	s_mov_b32 m0, s55
	s_nop 0
	global_load_lds_dwordx4 v146, s[84:85]
	v_mfma_f32_16x16x32_bf16 v[46:49], v[132:135], v[222:225], v[46:49]
	v_mfma_f32_16x16x32_bf16 v[42:45], v[140:143], v[222:225], v[42:45]
	v_mfma_f32_16x16x32_bf16 v[38:41], v[132:135], v[230:233], v[38:41]
	v_mfma_f32_16x16x32_bf16 v[34:37], v[140:143], v[230:233], v[34:37]
	v_mfma_f32_16x16x32_bf16 v[62:65], v[136:139], v[210:213], v[62:65]
	v_mfma_f32_16x16x32_bf16 v[58:61], v[186:189], v[210:213], v[58:61]
	s_mov_b32 m0, s56
	s_nop 0
	global_load_lds_dwordx4 v244, s[84:85]
	v_mfma_f32_16x16x32_bf16 v[54:57], v[136:139], v[218:221], v[54:57]
	v_mfma_f32_16x16x32_bf16 v[50:53], v[186:189], v[218:221], v[50:53]
	v_mfma_f32_16x16x32_bf16 v[46:49], v[136:139], v[226:229], v[46:49]
	v_mfma_f32_16x16x32_bf16 v[42:45], v[186:189], v[226:229], v[42:45]
	v_mfma_f32_16x16x32_bf16 v[38:41], v[136:139], v[234:237], v[38:41]
	v_mfma_f32_16x16x32_bf16 v[34:37], v[186:189], v[234:237], v[34:37]
	s_setprio 0
	s_setprio 1
	v_mfma_f32_16x16x32_bf16 v[30:33], v[190:193], v[206:209], v[30:33]
	s_add_i32 s71, 0, 0x18000
	v_mfma_f32_16x16x32_bf16 v[26:29], v[198:201], v[206:209], v[26:29]
	s_add_i32 s74, 0, 0x1c000
	v_mfma_f32_16x16x32_bf16 v[22:25], v[190:193], v[214:217], v[22:25]
	v_mfma_f32_16x16x32_bf16 v[18:21], v[198:201], v[214:217], v[18:21]
	v_mfma_f32_16x16x32_bf16 v[14:17], v[190:193], v[222:225], v[14:17]
	v_mfma_f32_16x16x32_bf16 v[10:13], v[198:201], v[222:225], v[10:13]
	v_mfma_f32_16x16x32_bf16 v[6:9], v[190:193], v[230:233], v[6:9]
	v_mfma_f32_16x16x32_bf16 v[2:5], v[198:201], v[230:233], v[2:5]
	v_mfma_f32_16x16x32_bf16 v[30:33], v[194:197], v[210:213], v[30:33]
	v_mfma_f32_16x16x32_bf16 v[26:29], v[202:205], v[210:213], v[26:29]
	v_mfma_f32_16x16x32_bf16 v[22:25], v[194:197], v[218:221], v[22:25]
	v_mfma_f32_16x16x32_bf16 v[18:21], v[202:205], v[218:221], v[18:21]
	v_mfma_f32_16x16x32_bf16 v[14:17], v[194:197], v[226:229], v[14:17]
	v_mfma_f32_16x16x32_bf16 v[10:13], v[202:205], v[226:229], v[10:13]
	v_mfma_f32_16x16x32_bf16 v[6:9], v[194:197], v[234:237], v[6:9]
	v_mfma_f32_16x16x32_bf16 v[2:5], v[202:205], v[234:237], v[2:5]
	s_setprio 0
	s_barrier
; #define PG8_STAGE(bufoff, gbase, voff) do { _Pragma("unroll") for (int _i = 0; _i < 2; ++_i) \
;         __builtin_amdgcn_global_load_lds((const unsigned*)((const char*)(gbase) + (voff)[_i]), (PG8_LAS unsigned*)(lds + (bufoff) + ldsw + _i * 8192), 16, 0, 0); } while (0)
; #define PG8_LDA(dst, b, h) do { _Pragma("unroll") for (int m = 0; m < 4; ++m) _Pragma("unroll") for (int k = 0; k < 2; ++k) dst[m][k] = *(const PG8_LAS bf16x8*)(lds + PG8_SA(b, h) + aoff + m * 2048 + k * 1024); } while (0)
; #define PG8_LDB(dst, b, h) do { _Pragma("unroll") for (int n = 0; n < 2; ++n) _Pragma("unroll") for (int k = 0; k < 2; ++k) dst[n][k] = *(const PG8_LAS bf16x8*)(lds + PG8_SB(b, h) + boff + n * 2048 + k * 1024); } while (0)
; #define PG8_MMA(ai, bj, At, Bt) do { __builtin_amdgcn_s_setprio(1); _Pragma("unroll") for (int m = 0; m < 4; ++m) _Pragma("unroll") for (int n = 0; n < 2; ++n) _Pragma("unroll") for (int k = 0; k < 2; ++k) \
;         acc[ai][bj][m][n] = __builtin_amdgcn_mfma_f32_16x16x32_bf16(Bt[n][k], At[m][k], acc[ai][bj][m][n], 0, 0, 0); __builtin_amdgcn_s_setprio(0); } while (0)
; #define PG8_WAIT_V(n) asm volatile("s_waitcnt vmcnt(" #n ")" ::: "memory")
; #define PG8_WAIT_L(n) asm volatile("s_waitcnt lgkmcnt(" #n ")" ::: "memory")
; #define PG8_BAR __builtin_amdgcn_s_barrier()
; #define PG8_SCHED __builtin_amdgcn_sched_barrier(0)
; template <class Epi, bool ALIGN_EPI, bool ABLK = false>
; __device__ __forceinline__ void gemm_phase(PG8_LAS unsigned char* lds, const Gemm g, const StaticOrder& S, const Epi& E) {
;     ...
;             PG8_LDB(B0, 1, 0); PG8_LDB(B1, 1, 1); PG8_SCHED; PG8_LDA(At, 1, 0); PG8_STAGE(PG8_SA(0, 1), a2 + hstepA, voffA);
;             PG8_WAIT_V(8); PG8_WAIT_L(0); PG8_BAR; PG8_MMA(0, 0, At, B0); PG8_MMA(0, 1, At, B1); PG8_BAR; PG8_SCHED;
;             PG8_LDA(At, 1, 1); PG8_STAGE(PG8_SB(1, 0), b3, voffB); PG8_STAGE(PG8_SB(1, 1), b3 + hstepB, voffB); PG8_STAGE(PG8_SA(1, 0), a3, voffA);
;             PG8_WAIT_V(8); PG8_WAIT_L(0); PG8_BAR; PG8_MMA(1, 0, At, B0); PG8_MMA(1, 1, At, B1); PG8_BAR; PG8_SCHED;
;         }
	ds_read_b128 v[132:135], v251 offset:32768
	ds_read_b128 v[136:139], v251 offset:33792
	ds_read_b128 v[140:143], v251 offset:34816
	ds_read_b128 v[186:189], v251 offset:35840
	ds_read_b128 v[190:193], v251 offset:49152
	ds_read_b128 v[194:197], v251 offset:50176
	ds_read_b128 v[198:201], v251 offset:51200
	ds_read_b128 v[202:205], v251 offset:52224
	s_mov_b64 s[72:73], 0x4000
	s_mov_b32 m0, s57
	s_mov_b64 s[72:73], 0x6000
	ds_read_b128 v[206:209], v183 offset:32768
	ds_read_b128 v[210:213], v183 offset:33792
	ds_read_b128 v[214:217], v183 offset:34816
	ds_read_b128 v[218:221], v183 offset:35840
	ds_read_b128 v[222:225], v183 offset:36864
	ds_read_b128 v[226:229], v183 offset:37888
	ds_read_b128 v[230:233], v183 offset:38912
	ds_read_b128 v[234:237], v183 offset:39936
	global_load_lds_dwordx4 v245, s[84:85]
	s_mov_b32 m0, s58
	s_nop 0
	global_load_lds_dwordx4 v246, s[84:85]
	s_waitcnt vmcnt(8)
	s_waitcnt lgkmcnt(0)
	s_barrier
	s_setprio 1
	s_waitcnt lgkmcnt(0)
	v_mfma_f32_16x16x32_bf16 v[126:129], v[132:135], v[206:209], v[126:129]
	v_mfma_f32_16x16x32_bf16 v[122:125], v[140:143], v[206:209], v[122:125]
	v_mfma_f32_16x16x32_bf16 v[118:121], v[132:135], v[214:217], v[118:121]
	v_mfma_f32_16x16x32_bf16 v[114:117], v[140:143], v[214:217], v[114:117]
	v_mfma_f32_16x16x32_bf16 v[110:113], v[132:135], v[222:225], v[110:113]
	v_mfma_f32_16x16x32_bf16 v[106:109], v[140:143], v[222:225], v[106:109]
	v_mfma_f32_16x16x32_bf16 v[102:105], v[132:135], v[230:233], v[102:105]
	v_mfma_f32_16x16x32_bf16 v[98:101], v[140:143], v[230:233], v[98:101]
	v_mfma_f32_16x16x32_bf16 v[126:129], v[136:139], v[210:213], v[126:129]
	v_mfma_f32_16x16x32_bf16 v[122:125], v[186:189], v[210:213], v[122:125]
	v_mfma_f32_16x16x32_bf16 v[118:121], v[136:139], v[218:221], v[118:121]
	v_mfma_f32_16x16x32_bf16 v[114:117], v[186:189], v[218:221], v[114:117]
	v_mfma_f32_16x16x32_bf16 v[110:113], v[136:139], v[226:229], v[110:113]
	v_mfma_f32_16x16x32_bf16 v[106:109], v[186:189], v[226:229], v[106:109]
	v_mfma_f32_16x16x32_bf16 v[102:105], v[136:139], v[234:237], v[102:105]
	v_mfma_f32_16x16x32_bf16 v[98:101], v[186:189], v[234:237], v[98:101]
	s_setprio 0
	s_setprio 1
	v_mfma_f32_16x16x32_bf16 v[94:97], v[190:193], v[206:209], v[94:97]
	s_add_i32 s71, s71, s9
	v_mfma_f32_16x16x32_bf16 v[90:93], v[198:201], v[206:209], v[90:93]
	s_add_u32 s86, s48, s28
	v_mfma_f32_16x16x32_bf16 v[86:89], v[190:193], v[214:217], v[86:89]
	s_addc_u32 s87, s49, s29
	v_mfma_f32_16x16x32_bf16 v[82:85], v[198:201], v[214:217], v[82:85]
	s_mov_b32 m0, s71
	v_mfma_f32_16x16x32_bf16 v[78:81], v[190:193], v[222:225], v[78:81]
	v_mfma_f32_16x16x32_bf16 v[74:77], v[198:201], v[222:225], v[74:77]
	v_mfma_f32_16x16x32_bf16 v[70:73], v[190:193], v[230:233], v[70:73]
	v_mfma_f32_16x16x32_bf16 v[66:69], v[198:201], v[230:233], v[66:69]
	v_mfma_f32_16x16x32_bf16 v[94:97], v[194:197], v[210:213], v[94:97]
	v_mfma_f32_16x16x32_bf16 v[90:93], v[202:205], v[210:213], v[90:93]
	v_mfma_f32_16x16x32_bf16 v[86:89], v[194:197], v[218:221], v[86:89]
	v_mfma_f32_16x16x32_bf16 v[82:85], v[202:205], v[218:221], v[82:85]
	v_mfma_f32_16x16x32_bf16 v[78:81], v[194:197], v[226:229], v[78:81]
	v_mfma_f32_16x16x32_bf16 v[74:77], v[202:205], v[226:229], v[74:77]
	v_mfma_f32_16x16x32_bf16 v[70:73], v[194:197], v[234:237], v[70:73]
	v_mfma_f32_16x16x32_bf16 v[66:69], v[202:205], v[234:237], v[66:69]
	s_setprio 0
	s_barrier
	ds_read_b128 v[206:209], v183 offset:49152
	ds_read_b128 v[210:213], v183 offset:50176
	ds_read_b128 v[214:217], v183 offset:51200
	ds_read_b128 v[218:221], v183 offset:52224
	ds_read_b128 v[222:225], v183 offset:53248
	ds_read_b128 v[226:229], v183 offset:54272
	ds_read_b128 v[230:233], v183 offset:55296
	ds_read_b128 v[234:237], v183 offset:56320
	global_load_lds_dwordx4 v148, s[86:87]
	s_add_i32 m0, s71, 0x2000
	s_add_u32 s48, s48, 0x40080
	s_addc_u32 s49, s49, 0
	s_add_i32 s71, s74, s9
	global_load_lds_dwordx4 v150, s[86:87]
	s_mov_b32 m0, s71
	s_nop 0
	global_load_lds_dwordx4 v148, s[48:49]
	s_add_i32 m0, s71, 0x2000
	s_nop 0
	global_load_lds_dwordx4 v150, s[48:49]
	s_waitcnt vmcnt(6)
	s_waitcnt lgkmcnt(0)
	s_barrier
	s_setprio 1
	s_waitcnt lgkmcnt(0)
	v_mfma_f32_16x16x32_bf16 v[62:65], v[132:135], v[206:209], v[62:65]
	v_mfma_f32_16x16x32_bf16 v[58:61], v[140:143], v[206:209], v[58:61]
	v_mfma_f32_16x16x32_bf16 v[54:57], v[132:135], v[214:217], v[54:57]
	v_mfma_f32_16x16x32_bf16 v[50:53], v[140:143], v[214:217], v[50:53]
	s_mov_b32 m0, s59
	s_nop 0
	global_load_lds_dwordx4 v247, s[84:85]
	v_mfma_f32_16x16x32_bf16 v[46:49], v[132:135], v[222:225], v[46:49]
	v_mfma_f32_16x16x32_bf16 v[42:45], v[140:143], v[222:225], v[42:45]
	v_mfma_f32_16x16x32_bf16 v[38:41], v[132:135], v[230:233], v[38:41]
	v_mfma_f32_16x16x32_bf16 v[34:37], v[140:143], v[230:233], v[34:37]
	v_mfma_f32_16x16x32_bf16 v[62:65], v[136:139], v[210:213], v[62:65]
	v_mfma_f32_16x16x32_bf16 v[58:61], v[186:189], v[210:213], v[58:61]
	s_mov_b32 m0, s61
	s_nop 0
	global_load_lds_dwordx4 v248, s[84:85]
	v_mfma_f32_16x16x32_bf16 v[54:57], v[136:139], v[218:221], v[54:57]
	v_mfma_f32_16x16x32_bf16 v[50:53], v[186:189], v[218:221], v[50:53]
	v_mfma_f32_16x16x32_bf16 v[46:49], v[136:139], v[226:229], v[46:49]
	v_mfma_f32_16x16x32_bf16 v[42:45], v[186:189], v[226:229], v[42:45]
	v_mfma_f32_16x16x32_bf16 v[38:41], v[136:139], v[234:237], v[38:41]
	v_mfma_f32_16x16x32_bf16 v[34:37], v[186:189], v[234:237], v[34:37]
	s_setprio 0
	s_setprio 1
	v_mfma_f32_16x16x32_bf16 v[30:33], v[190:193], v[206:209], v[30:33]
	s_add_i32 s70, s70, 2
	v_mfma_f32_16x16x32_bf16 v[26:29], v[198:201], v[206:209], v[26:29]
	s_add_u32 s68, s68, 0x100
	v_mfma_f32_16x16x32_bf16 v[22:25], v[190:193], v[214:217], v[22:25]
	s_addc_u32 s69, s69, 0
	v_mfma_f32_16x16x32_bf16 v[18:21], v[198:201], v[214:217], v[18:21]
	s_add_u32 s46, s46, 0x10000
	v_mfma_f32_16x16x32_bf16 v[14:17], v[190:193], v[222:225], v[14:17]
	s_addc_u32 s47, s47, 0
	v_mfma_f32_16x16x32_bf16 v[10:13], v[198:201], v[222:225], v[10:13]
	s_add_u32 s82, s82, 0x10000
	v_mfma_f32_16x16x32_bf16 v[6:9], v[190:193], v[230:233], v[6:9]
	s_addc_u32 s83, s83, 0
	v_mfma_f32_16x16x32_bf16 v[2:5], v[198:201], v[230:233], v[2:5]
	s_mov_b64 s[48:49], 0x10000
	v_mfma_f32_16x16x32_bf16 v[30:33], v[194:197], v[210:213], v[30:33]
	s_cmp_gt_u32 s70, 13
	v_mfma_f32_16x16x32_bf16 v[26:29], v[202:205], v[210:213], v[26:29]
	v_mfma_f32_16x16x32_bf16 v[22:25], v[194:197], v[218:221], v[22:25]
	v_mfma_f32_16x16x32_bf16 v[18:21], v[202:205], v[218:221], v[18:21]
	v_mfma_f32_16x16x32_bf16 v[14:17], v[194:197], v[226:229], v[14:17]
	v_mfma_f32_16x16x32_bf16 v[10:13], v[202:205], v[226:229], v[10:13]
	v_mfma_f32_16x16x32_bf16 v[6:9], v[194:197], v[234:237], v[6:9]
	v_mfma_f32_16x16x32_bf16 v[2:5], v[202:205], v[234:237], v[2:5]
	s_setprio 0
	s_barrier
	s_cbranch_scc0 .LBB0_402
	s_and_b64 vcc, exec, s[36:37]
	s_cbranch_vccz .LBB0_405
	s_barrier

; #define PG8_STAGE(bufoff, gbase, voff) do { _Pragma("unroll") for (int _i = 0; _i < 2; ++_i) \
;         __builtin_amdgcn_global_load_lds((const unsigned*)((const char*)(gbase) + (voff)[_i]), (PG8_LAS unsigned*)(lds + (bufoff) + ldsw + _i * 8192), 16, 0, 0); } while (0)
; #define PG8_LDA(dst, b, h) do { _Pragma("unroll") for (int m = 0; m < 4; ++m) _Pragma("unroll") for (int k = 0; k < 2; ++k) dst[m][k] = *(const PG8_LAS bf16x8*)(lds + PG8_SA(b, h) + aoff + m * 2048 + k * 1024); } while (0)
; #define PG8_LDB(dst, b, h) do { _Pragma("unroll") for (int n = 0; n < 2; ++n) _Pragma("unroll") for (int k = 0; k < 2; ++k) dst[n][k] = *(const PG8_LAS bf16x8*)(lds + PG8_SB(b, h) + boff + n * 2048 + k * 1024); } while (0)
; #define PG8_MMA(ai, bj, At, Bt) do { __builtin_amdgcn_s_setprio(1); _Pragma("unroll") for (int m = 0; m < 4; ++m) _Pragma("unroll") for (int n = 0; n < 2; ++n) _Pragma("unroll") for (int k = 0; k < 2; ++k) \
;         acc[ai][bj][m][n] = __builtin_amdgcn_mfma_f32_16x16x32_bf16(Bt[n][k], At[m][k], acc[ai][bj][m][n], 0, 0, 0); __builtin_amdgcn_s_setprio(0); } while (0)
; #define PG8_WAIT_V(n) asm volatile("s_waitcnt vmcnt(" #n ")" ::: "memory")
; #define PG8_WAIT_L(n) asm volatile("s_waitcnt lgkmcnt(" #n ")" ::: "memory")
; #define PG8_BAR __builtin_amdgcn_s_barrier()
; #define PG8_SCHED __builtin_amdgcn_sched_barrier(0)
; template <class Epi, bool ALIGN_EPI, bool ABLK = false>
; __device__ __forceinline__ void gemm_phase(PG8_LAS unsigned char* lds, const Gemm g, const StaticOrder& S, const Epi& E) {
;     ...
;             const char* a1 = cA + (size_t)(t + 1) * kstepA;
;             const char* a2 = last ? nA : cA + (size_t)(t + 2) * kstepA; const char* b2 = last ? nB : cB + (size_t)(t + 2) * kstepB;
;             const char* a3 = a2 + kstepA; const char* b3 = b2 + kstepB;
;             PG8_LDB(B0, 0, 0); PG8_LDB(B1, 0, 1); PG8_SCHED; PG8_LDA(At, 0, 0); PG8_STAGE(PG8_SA(1, 1), a1 + hstepA, voffA);
;             PG8_WAIT_V(8); PG8_WAIT_L(0); PG8_BAR; PG8_MMA(0, 0, At, B0); PG8_MMA(0, 1, At, B1); PG8_BAR; PG8_SCHED;
;             PG8_LDA(At, 0, 1); PG8_STAGE(PG8_SB(0, 0), b2, voffB); PG8_STAGE(PG8_SB(0, 1), b2 + hstepB, voffB); PG8_STAGE(PG8_SA(0, 0), a2, voffA);
;             PG8_WAIT_V(8); PG8_WAIT_L(0); PG8_BAR; PG8_MMA(1, 0, At, B0); PG8_MMA(1, 1, At, B1); PG8_BAR; PG8_SCHED;
.LBB0_818:
	ds_read_b128 v[132:135], v153
	ds_read_b128 v[136:139], v153 offset:1024
	ds_read_b128 v[140:143], v153 offset:2048
	ds_read_b128 v[144:147], v153 offset:3072
	ds_read_b128 v[148:151], v153 offset:16384
	ds_read_b128 v[178:181], v153 offset:17408
	ds_read_b128 v[182:185], v153 offset:18432
	ds_read_b128 v[212:215], v153 offset:19456
	s_add_u32 s12, s38, s10
	s_addc_u32 s13, s39, s11
	s_sub_u32 s98, s12, 0x10000
	s_subb_u32 s99, s13, 0
	s_cmp_eq_u32 s65, 12
	s_cselect_b32 s101, s33, s13
	s_cselect_b32 s100, s57, s12
	s_cselect_b32 s13, s55, s64
	s_cselect_b32 s12, s62, s63
	s_mov_b64 s[68:69], 0xc000
	s_add_i32 m0, s35, 0xc000
	s_mov_b64 s[68:69], 0xe000
	ds_read_b128 v[216:219], v205
	ds_read_b128 v[220:223], v205 offset:1024
	ds_read_b128 v[224:227], v205 offset:2048
	ds_read_b128 v[228:231], v205 offset:3072
	ds_read_b128 v[232:235], v205 offset:4096
	ds_read_b128 v[236:239], v205 offset:5120
	ds_read_b128 v[240:243], v205 offset:6144
	ds_read_b128 v[244:247], v205 offset:7168
	global_load_lds_dwordx4 v253, s[98:99]
	s_add_i32 m0, s35, 0xe000
	s_nop 0
	global_load_lds_dwordx4 v152, s[98:99]
	s_waitcnt vmcnt(8)
	s_waitcnt lgkmcnt(0)
	s_barrier
	s_setprio 1
	s_waitcnt lgkmcnt(0)
	v_mfma_f32_16x16x32_bf16 v[126:129], v[132:135], v[216:219], v[126:129]
	v_mfma_f32_16x16x32_bf16 v[122:125], v[140:143], v[216:219], v[122:125]
	v_mfma_f32_16x16x32_bf16 v[118:121], v[132:135], v[224:227], v[118:121]
	v_mfma_f32_16x16x32_bf16 v[114:117], v[140:143], v[224:227], v[114:117]
	v_mfma_f32_16x16x32_bf16 v[110:113], v[132:135], v[232:235], v[110:113]
	v_mfma_f32_16x16x32_bf16 v[106:109], v[140:143], v[232:235], v[106:109]
	v_mfma_f32_16x16x32_bf16 v[102:105], v[132:135], v[240:243], v[102:105]
	v_mfma_f32_16x16x32_bf16 v[98:101], v[140:143], v[240:243], v[98:101]
	v_mfma_f32_16x16x32_bf16 v[126:129], v[136:139], v[220:223], v[126:129]
	v_mfma_f32_16x16x32_bf16 v[122:125], v[144:147], v[220:223], v[122:125]
	v_mfma_f32_16x16x32_bf16 v[118:121], v[136:139], v[228:231], v[118:121]
	v_mfma_f32_16x16x32_bf16 v[114:117], v[144:147], v[228:231], v[114:117]
	v_mfma_f32_16x16x32_bf16 v[110:113], v[136:139], v[236:239], v[110:113]
	v_mfma_f32_16x16x32_bf16 v[106:109], v[144:147], v[236:239], v[106:109]
	v_mfma_f32_16x16x32_bf16 v[102:105], v[136:139], v[244:247], v[102:105]
	v_mfma_f32_16x16x32_bf16 v[98:101], v[144:147], v[244:247], v[98:101]
	s_setprio 0
	s_setprio 1
	v_mfma_f32_16x16x32_bf16 v[94:97], v[148:151], v[216:219], v[94:97]
	s_add_i32 s68, s42, s31
	v_mfma_f32_16x16x32_bf16 v[90:93], v[182:185], v[216:219], v[90:93]
	s_mov_b32 m0, s68
	v_mfma_f32_16x16x32_bf16 v[86:89], v[148:151], v[224:227], v[86:89]
	v_mfma_f32_16x16x32_bf16 v[82:85], v[182:185], v[224:227], v[82:85]
	v_mfma_f32_16x16x32_bf16 v[78:81], v[148:151], v[232:235], v[78:81]
	v_mfma_f32_16x16x32_bf16 v[74:77], v[182:185], v[232:235], v[74:77]
	v_mfma_f32_16x16x32_bf16 v[70:73], v[148:151], v[240:243], v[70:73]
	v_mfma_f32_16x16x32_bf16 v[66:69], v[182:185], v[240:243], v[66:69]
	v_mfma_f32_16x16x32_bf16 v[94:97], v[178:181], v[220:223], v[94:97]
	v_mfma_f32_16x16x32_bf16 v[90:93], v[212:215], v[220:223], v[90:93]
	v_mfma_f32_16x16x32_bf16 v[86:89], v[178:181], v[228:231], v[86:89]
	v_mfma_f32_16x16x32_bf16 v[82:85], v[212:215], v[228:231], v[82:85]
	v_mfma_f32_16x16x32_bf16 v[78:81], v[178:181], v[236:239], v[78:81]
	v_mfma_f32_16x16x32_bf16 v[74:77], v[212:215], v[236:239], v[74:77]
	v_mfma_f32_16x16x32_bf16 v[70:73], v[178:181], v[244:247], v[70:73]
	v_mfma_f32_16x16x32_bf16 v[66:69], v[212:215], v[244:247], v[66:69]
	s_setprio 0
	s_barrier
	ds_read_b128 v[216:219], v205 offset:16384
	ds_read_b128 v[220:223], v205 offset:17408
	ds_read_b128 v[224:227], v205 offset:18432
	ds_read_b128 v[228:231], v205 offset:19456
	ds_read_b128 v[232:235], v205 offset:20480
	ds_read_b128 v[236:239], v205 offset:21504
	ds_read_b128 v[240:243], v205 offset:22528
	ds_read_b128 v[244:247], v205 offset:23552
	global_load_lds_dwordx4 v156, s[12:13]
	s_add_i32 m0, s68, 0x2000
	s_add_u32 s68, s12, 0x40000
	s_addc_u32 s69, s13, 0
	s_add_i32 s70, s43, s31
	global_load_lds_dwordx4 v158, s[12:13]
	s_mov_b32 m0, s70
	s_nop 0
	global_load_lds_dwordx4 v156, s[68:69]
	s_add_i32 m0, s70, 0x2000
	s_nop 0
	global_load_lds_dwordx4 v158, s[68:69]
	s_waitcnt vmcnt(6)
	s_waitcnt lgkmcnt(0)
	s_barrier
	s_setprio 1
	s_waitcnt lgkmcnt(0)
	v_mfma_f32_16x16x32_bf16 v[62:65], v[132:135], v[216:219], v[62:65]
	v_mfma_f32_16x16x32_bf16 v[58:61], v[140:143], v[216:219], v[58:61]
	v_mfma_f32_16x16x32_bf16 v[54:57], v[132:135], v[224:227], v[54:57]
	v_mfma_f32_16x16x32_bf16 v[50:53], v[140:143], v[224:227], v[50:53]
	s_mov_b32 m0, s35
	s_nop 0
	global_load_lds_dwordx4 v154, s[100:101]
	v_mfma_f32_16x16x32_bf16 v[46:49], v[132:135], v[232:235], v[46:49]
	v_mfma_f32_16x16x32_bf16 v[42:45], v[140:143], v[232:235], v[42:45]
	v_mfma_f32_16x16x32_bf16 v[38:41], v[132:135], v[240:243], v[38:41]
	v_mfma_f32_16x16x32_bf16 v[34:37], v[140:143], v[240:243], v[34:37]
	v_mfma_f32_16x16x32_bf16 v[62:65], v[136:139], v[220:223], v[62:65]
	v_mfma_f32_16x16x32_bf16 v[58:61], v[144:147], v[220:223], v[58:61]
	s_mov_b32 m0, s18
	s_nop 0
	global_load_lds_dwordx4 v248, s[100:101]
	v_mfma_f32_16x16x32_bf16 v[54:57], v[136:139], v[228:231], v[54:57]
	v_mfma_f32_16x16x32_bf16 v[50:53], v[144:147], v[228:231], v[50:53]
	v_mfma_f32_16x16x32_bf16 v[46:49], v[136:139], v[236:239], v[46:49]
	v_mfma_f32_16x16x32_bf16 v[42:45], v[144:147], v[236:239], v[42:45]
	v_mfma_f32_16x16x32_bf16 v[38:41], v[136:139], v[244:247], v[38:41]
	v_mfma_f32_16x16x32_bf16 v[34:37], v[144:147], v[244:247], v[34:37]
	s_setprio 0
	s_setprio 1
	v_mfma_f32_16x16x32_bf16 v[30:33], v[148:151], v[216:219], v[30:33]
	s_add_i32 s68, 0, 0x18000
	v_mfma_f32_16x16x32_bf16 v[26:29], v[182:185], v[216:219], v[26:29]
	s_add_i32 s69, 0, 0x1c000
	v_mfma_f32_16x16x32_bf16 v[22:25], v[148:151], v[224:227], v[22:25]
	v_mfma_f32_16x16x32_bf16 v[18:21], v[182:185], v[224:227], v[18:21]
	v_mfma_f32_16x16x32_bf16 v[14:17], v[148:151], v[232:235], v[14:17]
	v_mfma_f32_16x16x32_bf16 v[10:13], v[182:185], v[232:235], v[10:13]
	v_mfma_f32_16x16x32_bf16 v[6:9], v[148:151], v[240:243], v[6:9]
	v_mfma_f32_16x16x32_bf16 v[2:5], v[182:185], v[240:243], v[2:5]
	v_mfma_f32_16x16x32_bf16 v[30:33], v[178:181], v[220:223], v[30:33]
	v_mfma_f32_16x16x32_bf16 v[26:29], v[212:215], v[220:223], v[26:29]
	v_mfma_f32_16x16x32_bf16 v[22:25], v[178:181], v[228:231], v[22:25]
	v_mfma_f32_16x16x32_bf16 v[18:21], v[212:215], v[228:231], v[18:21]
	v_mfma_f32_16x16x32_bf16 v[14:17], v[178:181], v[236:239], v[14:17]
	v_mfma_f32_16x16x32_bf16 v[10:13], v[212:215], v[236:239], v[10:13]
	v_mfma_f32_16x16x32_bf16 v[6:9], v[178:181], v[244:247], v[6:9]
	v_mfma_f32_16x16x32_bf16 v[2:5], v[212:215], v[244:247], v[2:5]
	s_setprio 0
	s_barrier
; #define PG8_STAGE(bufoff, gbase, voff) do { _Pragma("unroll") for (int _i = 0; _i < 2; ++_i) \
;         __builtin_amdgcn_global_load_lds((const unsigned*)((const char*)(gbase) + (voff)[_i]), (PG8_LAS unsigned*)(lds + (bufoff) + ldsw + _i * 8192), 16, 0, 0); } while (0)
; #define PG8_LDA(dst, b, h) do { _Pragma("unroll") for (int m = 0; m < 4; ++m) _Pragma("unroll") for (int k = 0; k < 2; ++k) dst[m][k] = *(const PG8_LAS bf16x8*)(lds + PG8_SA(b, h) + aoff + m * 2048 + k * 1024); } while (0)
; #define PG8_LDB(dst, b, h) do { _Pragma("unroll") for (int n = 0; n < 2; ++n) _Pragma("unroll") for (int k = 0; k < 2; ++k) dst[n][k] = *(const PG8_LAS bf16x8*)(lds + PG8_SB(b, h) + boff + n * 2048 + k * 1024); } while (0)
; #define PG8_MMA(ai, bj, At, Bt) do { __builtin_amdgcn_s_setprio(1); _Pragma("unroll") for (int m = 0; m < 4; ++m) _Pragma("unroll") for (int n = 0; n < 2; ++n) _Pragma("unroll") for (int k = 0; k < 2; ++k) \
;         acc[ai][bj][m][n] = __builtin_amdgcn_mfma_f32_16x16x32_bf16(Bt[n][k], At[m][k], acc[ai][bj][m][n], 0, 0, 0); __builtin_amdgcn_s_setprio(0); } while (0)
; #define PG8_WAIT_V(n) asm volatile("s_waitcnt vmcnt(" #n ")" ::: "memory")
; #define PG8_WAIT_L(n) asm volatile("s_waitcnt lgkmcnt(" #n ")" ::: "memory")
; #define PG8_BAR __builtin_amdgcn_s_barrier()
; #define PG8_SCHED __builtin_amdgcn_sched_barrier(0)
; template <class Epi, bool ALIGN_EPI, bool ABLK = false>
; __device__ __forceinline__ void gemm_phase(PG8_LAS unsigned char* lds, const Gemm g, const StaticOrder& S, const Epi& E) {
;     ...
;             PG8_LDB(B0, 1, 0); PG8_LDB(B1, 1, 1); PG8_SCHED; PG8_LDA(At, 1, 0); PG8_STAGE(PG8_SA(0, 1), a2 + hstepA, voffA);
;             PG8_WAIT_V(8); PG8_WAIT_L(0); PG8_BAR; PG8_MMA(0, 0, At, B0); PG8_MMA(0, 1, At, B1); PG8_BAR; PG8_SCHED;
;             PG8_LDA(At, 1, 1); PG8_STAGE(PG8_SB(1, 0), b3, voffB); PG8_STAGE(PG8_SB(1, 1), b3 + hstepB, voffB); PG8_STAGE(PG8_SA(1, 0), a3, voffA);
;             PG8_WAIT_V(8); PG8_WAIT_L(0); PG8_BAR; PG8_MMA(1, 0, At, B0); PG8_MMA(1, 1, At, B1); PG8_BAR; PG8_SCHED;
;         }
	ds_read_b128 v[132:135], v153 offset:32768
	ds_read_b128 v[136:139], v153 offset:33792
	ds_read_b128 v[140:143], v153 offset:34816
	ds_read_b128 v[144:147], v153 offset:35840
	ds_read_b128 v[148:151], v153 offset:49152
	ds_read_b128 v[178:181], v153 offset:50176
	ds_read_b128 v[182:185], v153 offset:51200
	ds_read_b128 v[212:215], v153 offset:52224
	s_mov_b64 s[66:67], 0x4000
	s_mov_b32 m0, s28
	s_mov_b64 s[66:67], 0x6000
	ds_read_b128 v[216:219], v205 offset:32768
	ds_read_b128 v[220:223], v205 offset:33792
	ds_read_b128 v[224:227], v205 offset:34816
	ds_read_b128 v[228:231], v205 offset:35840
	ds_read_b128 v[232:235], v205 offset:36864
	ds_read_b128 v[236:239], v205 offset:37888
	ds_read_b128 v[240:243], v205 offset:38912
	ds_read_b128 v[244:247], v205 offset:39936
	global_load_lds_dwordx4 v249, s[100:101]
	s_mov_b32 m0, s29
	s_nop 0
	global_load_lds_dwordx4 v250, s[100:101]
	s_waitcnt vmcnt(8)
	s_waitcnt lgkmcnt(0)
	s_barrier
	s_setprio 1
	s_waitcnt lgkmcnt(0)
	v_mfma_f32_16x16x32_bf16 v[126:129], v[132:135], v[216:219], v[126:129]
	v_mfma_f32_16x16x32_bf16 v[122:125], v[140:143], v[216:219], v[122:125]
	v_mfma_f32_16x16x32_bf16 v[118:121], v[132:135], v[224:227], v[118:121]
	v_mfma_f32_16x16x32_bf16 v[114:117], v[140:143], v[224:227], v[114:117]
	v_mfma_f32_16x16x32_bf16 v[110:113], v[132:135], v[232:235], v[110:113]
	v_mfma_f32_16x16x32_bf16 v[106:109], v[140:143], v[232:235], v[106:109]
	v_mfma_f32_16x16x32_bf16 v[102:105], v[132:135], v[240:243], v[102:105]
	v_mfma_f32_16x16x32_bf16 v[98:101], v[140:143], v[240:243], v[98:101]
	v_mfma_f32_16x16x32_bf16 v[126:129], v[136:139], v[220:223], v[126:129]
	v_mfma_f32_16x16x32_bf16 v[122:125], v[144:147], v[220:223], v[122:125]
	v_mfma_f32_16x16x32_bf16 v[118:121], v[136:139], v[228:231], v[118:121]
	v_mfma_f32_16x16x32_bf16 v[114:117], v[144:147], v[228:231], v[114:117]
	v_mfma_f32_16x16x32_bf16 v[110:113], v[136:139], v[236:239], v[110:113]
	v_mfma_f32_16x16x32_bf16 v[106:109], v[144:147], v[236:239], v[106:109]
	v_mfma_f32_16x16x32_bf16 v[102:105], v[136:139], v[244:247], v[102:105]
	v_mfma_f32_16x16x32_bf16 v[98:101], v[144:147], v[244:247], v[98:101]
	s_setprio 0
	s_setprio 1
	v_mfma_f32_16x16x32_bf16 v[94:97], v[148:151], v[216:219], v[94:97]
	s_add_i32 s66, s68, s31
	v_mfma_f32_16x16x32_bf16 v[90:93], v[182:185], v[216:219], v[90:93]
	s_add_u32 s12, s12, s46
	v_mfma_f32_16x16x32_bf16 v[86:89], v[148:151], v[224:227], v[86:89]
	s_addc_u32 s13, s13, s47
	v_mfma_f32_16x16x32_bf16 v[82:85], v[182:185], v[224:227], v[82:85]
	s_mov_b32 m0, s66
	v_mfma_f32_16x16x32_bf16 v[78:81], v[148:151], v[232:235], v[78:81]
	v_mfma_f32_16x16x32_bf16 v[74:77], v[182:185], v[232:235], v[74:77]
	v_mfma_f32_16x16x32_bf16 v[70:73], v[148:151], v[240:243], v[70:73]
	v_mfma_f32_16x16x32_bf16 v[66:69], v[182:185], v[240:243], v[66:69]
	v_mfma_f32_16x16x32_bf16 v[94:97], v[178:181], v[220:223], v[94:97]
	v_mfma_f32_16x16x32_bf16 v[90:93], v[212:215], v[220:223], v[90:93]
	v_mfma_f32_16x16x32_bf16 v[86:89], v[178:181], v[228:231], v[86:89]
	v_mfma_f32_16x16x32_bf16 v[82:85], v[212:215], v[228:231], v[82:85]
	v_mfma_f32_16x16x32_bf16 v[78:81], v[178:181], v[236:239], v[78:81]
	v_mfma_f32_16x16x32_bf16 v[74:77], v[212:215], v[236:239], v[74:77]
	v_mfma_f32_16x16x32_bf16 v[70:73], v[178:181], v[244:247], v[70:73]
	v_mfma_f32_16x16x32_bf16 v[66:69], v[212:215], v[244:247], v[66:69]
	s_setprio 0
	s_barrier
	ds_read_b128 v[216:219], v205 offset:49152
	ds_read_b128 v[220:223], v205 offset:50176
	ds_read_b128 v[224:227], v205 offset:51200
	ds_read_b128 v[228:231], v205 offset:52224
	ds_read_b128 v[232:235], v205 offset:53248
	ds_read_b128 v[236:239], v205 offset:54272
	ds_read_b128 v[240:243], v205 offset:55296
	ds_read_b128 v[244:247], v205 offset:56320
	global_load_lds_dwordx4 v156, s[12:13]
	s_add_i32 m0, s66, 0x2000
	s_add_i32 s66, s69, s31
	global_load_lds_dwordx4 v158, s[12:13]
	s_add_u32 s12, s12, 0x40000
	s_addc_u32 s13, s13, 0
	s_mov_b32 m0, s66
	s_nop 0
	global_load_lds_dwordx4 v156, s[12:13]
	s_add_i32 m0, s66, 0x2000
	s_nop 0
	global_load_lds_dwordx4 v158, s[12:13]
	s_waitcnt vmcnt(6)
	s_waitcnt lgkmcnt(0)
	s_barrier
	s_setprio 1
	s_waitcnt lgkmcnt(0)
	v_mfma_f32_16x16x32_bf16 v[62:65], v[132:135], v[216:219], v[62:65]
	v_mfma_f32_16x16x32_bf16 v[58:61], v[140:143], v[216:219], v[58:61]
	v_mfma_f32_16x16x32_bf16 v[54:57], v[132:135], v[224:227], v[54:57]
	v_mfma_f32_16x16x32_bf16 v[50:53], v[140:143], v[224:227], v[50:53]
	s_mov_b32 m0, s0
	s_nop 0
	global_load_lds_dwordx4 v251, s[100:101]
	v_mfma_f32_16x16x32_bf16 v[46:49], v[132:135], v[232:235], v[46:49]
	v_mfma_f32_16x16x32_bf16 v[42:45], v[140:143], v[232:235], v[42:45]
	v_mfma_f32_16x16x32_bf16 v[38:41], v[132:135], v[240:243], v[38:41]
	v_mfma_f32_16x16x32_bf16 v[34:37], v[140:143], v[240:243], v[34:37]
	v_mfma_f32_16x16x32_bf16 v[62:65], v[136:139], v[220:223], v[62:65]
	v_mfma_f32_16x16x32_bf16 v[58:61], v[144:147], v[220:223], v[58:61]
	s_mov_b32 m0, s1
	s_nop 0
	global_load_lds_dwordx4 v252, s[100:101]
	v_mfma_f32_16x16x32_bf16 v[54:57], v[136:139], v[228:231], v[54:57]
	v_mfma_f32_16x16x32_bf16 v[50:53], v[144:147], v[228:231], v[50:53]
	v_mfma_f32_16x16x32_bf16 v[46:49], v[136:139], v[236:239], v[46:49]
	v_mfma_f32_16x16x32_bf16 v[42:45], v[144:147], v[236:239], v[42:45]
	v_mfma_f32_16x16x32_bf16 v[38:41], v[136:139], v[244:247], v[38:41]
	v_mfma_f32_16x16x32_bf16 v[34:37], v[144:147], v[244:247], v[34:37]
	s_setprio 0
	s_setprio 1
	v_mfma_f32_16x16x32_bf16 v[30:33], v[148:151], v[216:219], v[30:33]
	s_add_i32 s65, s65, 2
	v_mfma_f32_16x16x32_bf16 v[26:29], v[182:185], v[216:219], v[26:29]
	s_add_u32 s63, s63, 0x100
	v_mfma_f32_16x16x32_bf16 v[22:25], v[148:151], v[224:227], v[22:25]
	s_addc_u32 s64, s64, 0
	v_mfma_f32_16x16x32_bf16 v[18:21], v[182:185], v[224:227], v[18:21]
	s_add_u32 s10, s10, 0x10000
	v_mfma_f32_16x16x32_bf16 v[14:17], v[148:151], v[232:235], v[14:17]
	s_addc_u32 s11, s11, 0
	v_mfma_f32_16x16x32_bf16 v[10:13], v[182:185], v[232:235], v[10:13]
	s_mov_b64 s[12:13], 0x10000
	v_mfma_f32_16x16x32_bf16 v[6:9], v[148:151], v[240:243], v[6:9]
	s_cmp_gt_u32 s65, 13
	v_mfma_f32_16x16x32_bf16 v[2:5], v[182:185], v[240:243], v[2:5]
	v_mfma_f32_16x16x32_bf16 v[30:33], v[178:181], v[220:223], v[30:33]
	v_mfma_f32_16x16x32_bf16 v[26:29], v[212:215], v[220:223], v[26:29]
	v_mfma_f32_16x16x32_bf16 v[22:25], v[178:181], v[228:231], v[22:25]
	v_mfma_f32_16x16x32_bf16 v[18:21], v[212:215], v[228:231], v[18:21]
	v_mfma_f32_16x16x32_bf16 v[14:17], v[178:181], v[236:239], v[14:17]
	v_mfma_f32_16x16x32_bf16 v[10:13], v[212:215], v[236:239], v[10:13]
	v_mfma_f32_16x16x32_bf16 v[6:9], v[178:181], v[244:247], v[6:9]
	v_mfma_f32_16x16x32_bf16 v[2:5], v[212:215], v[244:247], v[2:5]
	s_setprio 0
	s_barrier
	s_cbranch_scc0 .LBB0_818
	s_and_b64 vcc, exec, s[52:53]
	s_cbranch_vccz .LBB0_821
	s_barrier

; #define PG8_STAGE(bufoff, gbase, voff) do { _Pragma("unroll") for (int _i = 0; _i < 2; ++_i) \
;         __builtin_amdgcn_global_load_lds((const unsigned*)((const char*)(gbase) + (voff)[_i]), (PG8_LAS unsigned*)(lds + (bufoff) + ldsw + _i * 8192), 16, 0, 0); } while (0)
; #define PG8_LDA(dst, b, h) do { _Pragma("unroll") for (int m = 0; m < 4; ++m) _Pragma("unroll") for (int k = 0; k < 2; ++k) dst[m][k] = *(const PG8_LAS bf16x8*)(lds + PG8_SA(b, h) + aoff + m * 2048 + k * 1024); } while (0)
; #define PG8_LDB(dst, b, h) do { _Pragma("unroll") for (int n = 0; n < 2; ++n) _Pragma("unroll") for (int k = 0; k < 2; ++k) dst[n][k] = *(const PG8_LAS bf16x8*)(lds + PG8_SB(b, h) + boff + n * 2048 + k * 1024); } while (0)
; #define PG8_MMA(ai, bj, At, Bt) do { __builtin_amdgcn_s_setprio(1); _Pragma("unroll") for (int m = 0; m < 4; ++m) _Pragma("unroll") for (int n = 0; n < 2; ++n) _Pragma("unroll") for (int k = 0; k < 2; ++k) \
;         acc[ai][bj][m][n] = __builtin_amdgcn_mfma_f32_16x16x32_bf16(Bt[n][k], At[m][k], acc[ai][bj][m][n], 0, 0, 0); __builtin_amdgcn_s_setprio(0); } while (0)
; #define PG8_WAIT_V(n) asm volatile("s_waitcnt vmcnt(" #n ")" ::: "memory")
; #define PG8_WAIT_L(n) asm volatile("s_waitcnt lgkmcnt(" #n ")" ::: "memory")
; #define PG8_BAR __builtin_amdgcn_s_barrier()
; #define PG8_SCHED __builtin_amdgcn_sched_barrier(0)
; template <class Epi, bool ALIGN_EPI, bool ABLK = false>
; __device__ __forceinline__ void gemm_phase(PG8_LAS unsigned char* lds, const Gemm g, const StaticOrder& S, const Epi& E) {
;     ...
;             const char* a1 = cA + (size_t)(t + 1) * kstepA;
;             const char* a2 = last ? nA : cA + (size_t)(t + 2) * kstepA; const char* b2 = last ? nB : cB + (size_t)(t + 2) * kstepB;
;             const char* a3 = a2 + kstepA; const char* b3 = b2 + kstepB;
;             PG8_LDB(B0, 0, 0); PG8_LDB(B1, 0, 1); PG8_SCHED; PG8_LDA(At, 0, 0); PG8_STAGE(PG8_SA(1, 1), a1 + hstepA, voffA);
;             PG8_WAIT_V(8); PG8_WAIT_L(0); PG8_BAR; PG8_MMA(0, 0, At, B0); PG8_MMA(0, 1, At, B1); PG8_BAR; PG8_SCHED;
;             PG8_LDA(At, 0, 1); PG8_STAGE(PG8_SB(0, 0), b2, voffB); PG8_STAGE(PG8_SB(0, 1), b2 + hstepB, voffB); PG8_STAGE(PG8_SA(0, 0), a2, voffA);
;             PG8_WAIT_V(8); PG8_WAIT_L(0); PG8_BAR; PG8_MMA(1, 0, At, B0); PG8_MMA(1, 1, At, B1); PG8_BAR; PG8_SCHED;
.LBB0_2495:
	ds_read_b128 v[132:135], v251
	ds_read_b128 v[178:181], v251 offset:1024
	ds_read_b128 v[182:185], v251 offset:2048
	ds_read_b128 v[186:189], v251 offset:3072
	ds_read_b128 v[190:193], v251 offset:16384
	ds_read_b128 v[194:197], v251 offset:17408
	ds_read_b128 v[198:201], v251 offset:18432
	ds_read_b128 v[202:205], v251 offset:19456
	s_add_u32 s60, s24, s58
	s_addc_u32 s61, s25, s59
	s_sub_u32 s98, s60, 0x10000
	s_subb_u32 s99, s61, 0
	s_cmp_eq_u32 s83, 12
	s_cselect_b32 s101, s53, s61
	s_cselect_b32 s100, s79, s60
	s_cselect_b32 s61, s51, s82
	s_cselect_b32 s60, s80, s81
	s_add_i32 m0, s66, 0xc000
	ds_read_b128 v[206:209], v176
	ds_read_b128 v[210:213], v176 offset:1024
	ds_read_b128 v[214:217], v176 offset:2048
	ds_read_b128 v[218:221], v176 offset:3072
	ds_read_b128 v[222:225], v176 offset:4096
	ds_read_b128 v[226:229], v176 offset:5120
	ds_read_b128 v[230:233], v176 offset:6144
	ds_read_b128 v[234:237], v176 offset:7168
	global_load_lds_dwordx4 v249, s[98:99]
	s_add_i32 m0, s66, 0xe000
	s_nop 0
	global_load_lds_dwordx4 v250, s[98:99]
	s_waitcnt vmcnt(8)
	s_waitcnt lgkmcnt(0)
	s_barrier
	s_setprio 1
	s_waitcnt lgkmcnt(0)
	v_mfma_f32_16x16x32_bf16 v[126:129], v[132:135], v[206:209], v[126:129]
	v_mfma_f32_16x16x32_bf16 v[122:125], v[182:185], v[206:209], v[122:125]
	v_mfma_f32_16x16x32_bf16 v[118:121], v[132:135], v[214:217], v[118:121]
	v_mfma_f32_16x16x32_bf16 v[114:117], v[182:185], v[214:217], v[114:117]
	v_mfma_f32_16x16x32_bf16 v[110:113], v[132:135], v[222:225], v[110:113]
	v_mfma_f32_16x16x32_bf16 v[106:109], v[182:185], v[222:225], v[106:109]
	v_mfma_f32_16x16x32_bf16 v[102:105], v[132:135], v[230:233], v[102:105]
	v_mfma_f32_16x16x32_bf16 v[98:101], v[182:185], v[230:233], v[98:101]
	v_mfma_f32_16x16x32_bf16 v[126:129], v[178:181], v[210:213], v[126:129]
	v_mfma_f32_16x16x32_bf16 v[122:125], v[186:189], v[210:213], v[122:125]
	v_mfma_f32_16x16x32_bf16 v[118:121], v[178:181], v[218:221], v[118:121]
	v_mfma_f32_16x16x32_bf16 v[114:117], v[186:189], v[218:221], v[114:117]
	v_mfma_f32_16x16x32_bf16 v[110:113], v[178:181], v[226:229], v[110:113]
	v_mfma_f32_16x16x32_bf16 v[106:109], v[186:189], v[226:229], v[106:109]
	v_mfma_f32_16x16x32_bf16 v[102:105], v[178:181], v[234:237], v[102:105]
	v_mfma_f32_16x16x32_bf16 v[98:101], v[186:189], v[234:237], v[98:101]
	s_setprio 0
	s_setprio 1
	v_mfma_f32_16x16x32_bf16 v[94:97], v[190:193], v[206:209], v[94:97]
	s_add_i32 s86, s75, s9
	v_mfma_f32_16x16x32_bf16 v[90:93], v[198:201], v[206:209], v[90:93]
	s_mov_b32 m0, s86
	v_mfma_f32_16x16x32_bf16 v[86:89], v[190:193], v[214:217], v[86:89]
	v_mfma_f32_16x16x32_bf16 v[82:85], v[198:201], v[214:217], v[82:85]
	v_mfma_f32_16x16x32_bf16 v[78:81], v[190:193], v[222:225], v[78:81]
	v_mfma_f32_16x16x32_bf16 v[74:77], v[198:201], v[222:225], v[74:77]
	v_mfma_f32_16x16x32_bf16 v[70:73], v[190:193], v[230:233], v[70:73]
	v_mfma_f32_16x16x32_bf16 v[66:69], v[198:201], v[230:233], v[66:69]
	v_mfma_f32_16x16x32_bf16 v[94:97], v[194:197], v[210:213], v[94:97]
	v_mfma_f32_16x16x32_bf16 v[90:93], v[202:205], v[210:213], v[90:93]
	v_mfma_f32_16x16x32_bf16 v[86:89], v[194:197], v[218:221], v[86:89]
	v_mfma_f32_16x16x32_bf16 v[82:85], v[202:205], v[218:221], v[82:85]
	v_mfma_f32_16x16x32_bf16 v[78:81], v[194:197], v[226:229], v[78:81]
	v_mfma_f32_16x16x32_bf16 v[74:77], v[202:205], v[226:229], v[74:77]
	v_mfma_f32_16x16x32_bf16 v[70:73], v[194:197], v[234:237], v[70:73]
	v_mfma_f32_16x16x32_bf16 v[66:69], v[202:205], v[234:237], v[66:69]
	s_setprio 0
	s_barrier
	ds_read_b128 v[206:209], v176 offset:16384
	ds_read_b128 v[210:213], v176 offset:17408
	ds_read_b128 v[214:217], v176 offset:18432
	ds_read_b128 v[218:221], v176 offset:19456
	ds_read_b128 v[222:225], v176 offset:20480
	ds_read_b128 v[226:229], v176 offset:21504
	ds_read_b128 v[230:233], v176 offset:22528
	ds_read_b128 v[234:237], v176 offset:23552
	global_load_lds_dwordx4 v140, s[60:61]
	s_add_i32 m0, s86, 0x2000
	s_add_u32 s86, s60, 0x40000
	s_addc_u32 s87, s61, 0
	s_add_i32 s88, s76, s9
	global_load_lds_dwordx4 v142, s[60:61]
	s_mov_b32 m0, s88
	s_nop 0
	global_load_lds_dwordx4 v140, s[86:87]
	s_add_i32 m0, s88, 0x2000
	s_nop 0
	global_load_lds_dwordx4 v142, s[86:87]
	s_waitcnt vmcnt(6)
	s_waitcnt lgkmcnt(0)
	s_barrier
	s_setprio 1
	s_waitcnt lgkmcnt(0)
	v_mfma_f32_16x16x32_bf16 v[62:65], v[132:135], v[206:209], v[62:65]
	v_mfma_f32_16x16x32_bf16 v[58:61], v[182:185], v[206:209], v[58:61]
	v_mfma_f32_16x16x32_bf16 v[54:57], v[132:135], v[214:217], v[54:57]
	v_mfma_f32_16x16x32_bf16 v[50:53], v[182:185], v[214:217], v[50:53]
	s_mov_b32 m0, s66
	s_nop 0
	global_load_lds_dwordx4 v138, s[100:101]
	v_mfma_f32_16x16x32_bf16 v[46:49], v[132:135], v[222:225], v[46:49]
	v_mfma_f32_16x16x32_bf16 v[42:45], v[182:185], v[222:225], v[42:45]
	v_mfma_f32_16x16x32_bf16 v[38:41], v[132:135], v[230:233], v[38:41]
	v_mfma_f32_16x16x32_bf16 v[34:37], v[182:185], v[230:233], v[34:37]
	v_mfma_f32_16x16x32_bf16 v[62:65], v[178:181], v[210:213], v[62:65]
	v_mfma_f32_16x16x32_bf16 v[58:61], v[186:189], v[210:213], v[58:61]
	s_mov_b32 m0, s67
	s_nop 0
	global_load_lds_dwordx4 v244, s[100:101]
	v_mfma_f32_16x16x32_bf16 v[54:57], v[178:181], v[218:221], v[54:57]
	v_mfma_f32_16x16x32_bf16 v[50:53], v[186:189], v[218:221], v[50:53]
	v_mfma_f32_16x16x32_bf16 v[46:49], v[178:181], v[226:229], v[46:49]
	v_mfma_f32_16x16x32_bf16 v[42:45], v[186:189], v[226:229], v[42:45]
	v_mfma_f32_16x16x32_bf16 v[38:41], v[178:181], v[234:237], v[38:41]
	v_mfma_f32_16x16x32_bf16 v[34:37], v[186:189], v[234:237], v[34:37]
	s_setprio 0
	s_setprio 1
	v_mfma_f32_16x16x32_bf16 v[30:33], v[190:193], v[206:209], v[30:33]
	s_add_i32 s84, 0, 0x18000
	v_mfma_f32_16x16x32_bf16 v[26:29], v[198:201], v[206:209], v[26:29]
	s_add_i32 s85, 0, 0x1c000
	v_mfma_f32_16x16x32_bf16 v[22:25], v[190:193], v[214:217], v[22:25]
	v_mfma_f32_16x16x32_bf16 v[18:21], v[198:201], v[214:217], v[18:21]
	v_mfma_f32_16x16x32_bf16 v[14:17], v[190:193], v[222:225], v[14:17]
	v_mfma_f32_16x16x32_bf16 v[10:13], v[198:201], v[222:225], v[10:13]
	v_mfma_f32_16x16x32_bf16 v[6:9], v[190:193], v[230:233], v[6:9]
	v_mfma_f32_16x16x32_bf16 v[2:5], v[198:201], v[230:233], v[2:5]
	v_mfma_f32_16x16x32_bf16 v[30:33], v[194:197], v[210:213], v[30:33]
	v_mfma_f32_16x16x32_bf16 v[26:29], v[202:205], v[210:213], v[26:29]
	v_mfma_f32_16x16x32_bf16 v[22:25], v[194:197], v[218:221], v[22:25]
	v_mfma_f32_16x16x32_bf16 v[18:21], v[202:205], v[218:221], v[18:21]
	v_mfma_f32_16x16x32_bf16 v[14:17], v[194:197], v[226:229], v[14:17]
	v_mfma_f32_16x16x32_bf16 v[10:13], v[202:205], v[226:229], v[10:13]
	v_mfma_f32_16x16x32_bf16 v[6:9], v[194:197], v[234:237], v[6:9]
	v_mfma_f32_16x16x32_bf16 v[2:5], v[202:205], v[234:237], v[2:5]
	s_setprio 0
	s_barrier
; #define PG8_STAGE(bufoff, gbase, voff) do { _Pragma("unroll") for (int _i = 0; _i < 2; ++_i) \
;         __builtin_amdgcn_global_load_lds((const unsigned*)((const char*)(gbase) + (voff)[_i]), (PG8_LAS unsigned*)(lds + (bufoff) + ldsw + _i * 8192), 16, 0, 0); } while (0)
; #define PG8_LDA(dst, b, h) do { _Pragma("unroll") for (int m = 0; m < 4; ++m) _Pragma("unroll") for (int k = 0; k < 2; ++k) dst[m][k] = *(const PG8_LAS bf16x8*)(lds + PG8_SA(b, h) + aoff + m * 2048 + k * 1024); } while (0)
; #define PG8_LDB(dst, b, h) do { _Pragma("unroll") for (int n = 0; n < 2; ++n) _Pragma("unroll") for (int k = 0; k < 2; ++k) dst[n][k] = *(const PG8_LAS bf16x8*)(lds + PG8_SB(b, h) + boff + n * 2048 + k * 1024); } while (0)
; #define PG8_MMA(ai, bj, At, Bt) do { __builtin_amdgcn_s_setprio(1); _Pragma("unroll") for (int m = 0; m < 4; ++m) _Pragma("unroll") for (int n = 0; n < 2; ++n) _Pragma("unroll") for (int k = 0; k < 2; ++k) \
;         acc[ai][bj][m][n] = __builtin_amdgcn_mfma_f32_16x16x32_bf16(Bt[n][k], At[m][k], acc[ai][bj][m][n], 0, 0, 0); __builtin_amdgcn_s_setprio(0); } while (0)
; #define PG8_WAIT_V(n) asm volatile("s_waitcnt vmcnt(" #n ")" ::: "memory")
; #define PG8_WAIT_L(n) asm volatile("s_waitcnt lgkmcnt(" #n ")" ::: "memory")
; #define PG8_BAR __builtin_amdgcn_s_barrier()
; #define PG8_SCHED __builtin_amdgcn_sched_barrier(0)
; template <class Epi, bool ALIGN_EPI, bool ABLK = false>
; __device__ __forceinline__ void gemm_phase(PG8_LAS unsigned char* lds, const Gemm g, const StaticOrder& S, const Epi& E) {
;     ...
;             PG8_LDB(B0, 1, 0); PG8_LDB(B1, 1, 1); PG8_SCHED; PG8_LDA(At, 1, 0); PG8_STAGE(PG8_SA(0, 1), a2 + hstepA, voffA);
;             PG8_WAIT_V(8); PG8_WAIT_L(0); PG8_BAR; PG8_MMA(0, 0, At, B0); PG8_MMA(0, 1, At, B1); PG8_BAR; PG8_SCHED;
;             PG8_LDA(At, 1, 1); PG8_STAGE(PG8_SB(1, 0), b3, voffB); PG8_STAGE(PG8_SB(1, 1), b3 + hstepB, voffB); PG8_STAGE(PG8_SA(1, 0), a3, voffA);
;             PG8_WAIT_V(8); PG8_WAIT_L(0); PG8_BAR; PG8_MMA(1, 0, At, B0); PG8_MMA(1, 1, At, B1); PG8_BAR; PG8_SCHED;
	ds_read_b128 v[132:135], v251 offset:32768
	ds_read_b128 v[178:181], v251 offset:33792
	ds_read_b128 v[182:185], v251 offset:34816
	ds_read_b128 v[186:189], v251 offset:35840
	ds_read_b128 v[190:193], v251 offset:49152
	ds_read_b128 v[194:197], v251 offset:50176
	ds_read_b128 v[198:201], v251 offset:51200
	ds_read_b128 v[202:205], v251 offset:52224
	s_mov_b32 m0, s68
	ds_read_b128 v[206:209], v176 offset:32768
	ds_read_b128 v[210:213], v176 offset:33792
	ds_read_b128 v[214:217], v176 offset:34816
	ds_read_b128 v[218:221], v176 offset:35840
	ds_read_b128 v[222:225], v176 offset:36864
	ds_read_b128 v[226:229], v176 offset:37888
	ds_read_b128 v[230:233], v176 offset:38912
	ds_read_b128 v[234:237], v176 offset:39936
	global_load_lds_dwordx4 v245, s[100:101]
	s_mov_b32 m0, s69
	s_nop 0
	global_load_lds_dwordx4 v246, s[100:101]
	s_waitcnt vmcnt(8)
	s_waitcnt lgkmcnt(0)
	s_barrier
	s_setprio 1
	s_waitcnt lgkmcnt(0)
	v_mfma_f32_16x16x32_bf16 v[126:129], v[132:135], v[206:209], v[126:129]
	v_mfma_f32_16x16x32_bf16 v[122:125], v[182:185], v[206:209], v[122:125]
	v_mfma_f32_16x16x32_bf16 v[118:121], v[132:135], v[214:217], v[118:121]
	v_mfma_f32_16x16x32_bf16 v[114:117], v[182:185], v[214:217], v[114:117]
	v_mfma_f32_16x16x32_bf16 v[110:113], v[132:135], v[222:225], v[110:113]
	v_mfma_f32_16x16x32_bf16 v[106:109], v[182:185], v[222:225], v[106:109]
	v_mfma_f32_16x16x32_bf16 v[102:105], v[132:135], v[230:233], v[102:105]
	v_mfma_f32_16x16x32_bf16 v[98:101], v[182:185], v[230:233], v[98:101]
	v_mfma_f32_16x16x32_bf16 v[126:129], v[178:181], v[210:213], v[126:129]
	v_mfma_f32_16x16x32_bf16 v[122:125], v[186:189], v[210:213], v[122:125]
	v_mfma_f32_16x16x32_bf16 v[118:121], v[178:181], v[218:221], v[118:121]
	v_mfma_f32_16x16x32_bf16 v[114:117], v[186:189], v[218:221], v[114:117]
	v_mfma_f32_16x16x32_bf16 v[110:113], v[178:181], v[226:229], v[110:113]
	v_mfma_f32_16x16x32_bf16 v[106:109], v[186:189], v[226:229], v[106:109]
	v_mfma_f32_16x16x32_bf16 v[102:105], v[178:181], v[234:237], v[102:105]
	v_mfma_f32_16x16x32_bf16 v[98:101], v[186:189], v[234:237], v[98:101]
	s_setprio 0
	s_setprio 1
	v_mfma_f32_16x16x32_bf16 v[94:97], v[190:193], v[206:209], v[94:97]
	s_add_i32 s84, s84, s9
	v_mfma_f32_16x16x32_bf16 v[90:93], v[198:201], v[206:209], v[90:93]
	s_add_u32 s60, s60, s28
	v_mfma_f32_16x16x32_bf16 v[86:89], v[190:193], v[214:217], v[86:89]
	s_addc_u32 s61, s61, s29
	v_mfma_f32_16x16x32_bf16 v[82:85], v[198:201], v[214:217], v[82:85]
	s_mov_b32 m0, s84
	v_mfma_f32_16x16x32_bf16 v[78:81], v[190:193], v[222:225], v[78:81]
	v_mfma_f32_16x16x32_bf16 v[74:77], v[198:201], v[222:225], v[74:77]
	v_mfma_f32_16x16x32_bf16 v[70:73], v[190:193], v[230:233], v[70:73]
	v_mfma_f32_16x16x32_bf16 v[66:69], v[198:201], v[230:233], v[66:69]
	v_mfma_f32_16x16x32_bf16 v[94:97], v[194:197], v[210:213], v[94:97]
	v_mfma_f32_16x16x32_bf16 v[90:93], v[202:205], v[210:213], v[90:93]
	v_mfma_f32_16x16x32_bf16 v[86:89], v[194:197], v[218:221], v[86:89]
	v_mfma_f32_16x16x32_bf16 v[82:85], v[202:205], v[218:221], v[82:85]
	v_mfma_f32_16x16x32_bf16 v[78:81], v[194:197], v[226:229], v[78:81]
	v_mfma_f32_16x16x32_bf16 v[74:77], v[202:205], v[226:229], v[74:77]
	v_mfma_f32_16x16x32_bf16 v[70:73], v[194:197], v[234:237], v[70:73]
	v_mfma_f32_16x16x32_bf16 v[66:69], v[202:205], v[234:237], v[66:69]
	s_setprio 0
	s_barrier
	ds_read_b128 v[206:209], v176 offset:49152
	ds_read_b128 v[210:213], v176 offset:50176
	ds_read_b128 v[214:217], v176 offset:51200
	ds_read_b128 v[218:221], v176 offset:52224
	ds_read_b128 v[222:225], v176 offset:53248
	ds_read_b128 v[226:229], v176 offset:54272
	ds_read_b128 v[230:233], v176 offset:55296
	ds_read_b128 v[234:237], v176 offset:56320
	global_load_lds_dwordx4 v140, s[60:61]
	s_add_i32 m0, s84, 0x2000
	s_add_i32 s84, s85, s9
	global_load_lds_dwordx4 v142, s[60:61]
	s_add_u32 s60, s60, 0x40000
	s_addc_u32 s61, s61, 0
	s_mov_b32 m0, s84
	s_nop 0
	global_load_lds_dwordx4 v140, s[60:61]
	s_add_i32 m0, s84, 0x2000
	s_nop 0
	global_load_lds_dwordx4 v142, s[60:61]
	s_waitcnt vmcnt(6)
	s_waitcnt lgkmcnt(0)
	s_barrier
	s_setprio 1
	s_waitcnt lgkmcnt(0)
	v_mfma_f32_16x16x32_bf16 v[62:65], v[132:135], v[206:209], v[62:65]
	v_mfma_f32_16x16x32_bf16 v[58:61], v[182:185], v[206:209], v[58:61]
	v_mfma_f32_16x16x32_bf16 v[54:57], v[132:135], v[214:217], v[54:57]
	v_mfma_f32_16x16x32_bf16 v[50:53], v[182:185], v[214:217], v[50:53]
	s_mov_b32 m0, s70
	s_nop 0
	global_load_lds_dwordx4 v247, s[100:101]
	v_mfma_f32_16x16x32_bf16 v[46:49], v[132:135], v[222:225], v[46:49]
	v_mfma_f32_16x16x32_bf16 v[42:45], v[182:185], v[222:225], v[42:45]
	v_mfma_f32_16x16x32_bf16 v[38:41], v[132:135], v[230:233], v[38:41]
	v_mfma_f32_16x16x32_bf16 v[34:37], v[182:185], v[230:233], v[34:37]
	v_mfma_f32_16x16x32_bf16 v[62:65], v[178:181], v[210:213], v[62:65]
	v_mfma_f32_16x16x32_bf16 v[58:61], v[186:189], v[210:213], v[58:61]
	s_mov_b32 m0, s72
	s_nop 0
	global_load_lds_dwordx4 v248, s[100:101]
	v_mfma_f32_16x16x32_bf16 v[54:57], v[178:181], v[218:221], v[54:57]
	v_mfma_f32_16x16x32_bf16 v[50:53], v[186:189], v[218:221], v[50:53]
	v_mfma_f32_16x16x32_bf16 v[46:49], v[178:181], v[226:229], v[46:49]
	v_mfma_f32_16x16x32_bf16 v[42:45], v[186:189], v[226:229], v[42:45]
	v_mfma_f32_16x16x32_bf16 v[38:41], v[178:181], v[234:237], v[38:41]
	v_mfma_f32_16x16x32_bf16 v[34:37], v[186:189], v[234:237], v[34:37]
	s_setprio 0
	s_setprio 1
	v_mfma_f32_16x16x32_bf16 v[30:33], v[190:193], v[206:209], v[30:33]
	s_add_i32 s83, s83, 2
	v_mfma_f32_16x16x32_bf16 v[26:29], v[198:201], v[206:209], v[26:29]
	s_add_u32 s81, s81, 0x100
	v_mfma_f32_16x16x32_bf16 v[22:25], v[190:193], v[214:217], v[22:25]
	s_addc_u32 s82, s82, 0
	v_mfma_f32_16x16x32_bf16 v[18:21], v[198:201], v[214:217], v[18:21]
	s_add_u32 s58, s58, 0x10000
	v_mfma_f32_16x16x32_bf16 v[14:17], v[190:193], v[222:225], v[14:17]
	s_addc_u32 s59, s59, 0
	v_mfma_f32_16x16x32_bf16 v[10:13], v[198:201], v[222:225], v[10:13]
	s_cmp_gt_u32 s83, 13
	v_mfma_f32_16x16x32_bf16 v[6:9], v[190:193], v[230:233], v[6:9]
	v_mfma_f32_16x16x32_bf16 v[2:5], v[198:201], v[230:233], v[2:5]
	v_mfma_f32_16x16x32_bf16 v[30:33], v[194:197], v[210:213], v[30:33]
	v_mfma_f32_16x16x32_bf16 v[26:29], v[202:205], v[210:213], v[26:29]
	v_mfma_f32_16x16x32_bf16 v[22:25], v[194:197], v[218:221], v[22:25]
	v_mfma_f32_16x16x32_bf16 v[18:21], v[202:205], v[218:221], v[18:21]
	v_mfma_f32_16x16x32_bf16 v[14:17], v[194:197], v[226:229], v[14:17]
	v_mfma_f32_16x16x32_bf16 v[10:13], v[202:205], v[226:229], v[10:13]
	v_mfma_f32_16x16x32_bf16 v[6:9], v[194:197], v[234:237], v[6:9]
	v_mfma_f32_16x16x32_bf16 v[2:5], v[202:205], v[234:237], v[2:5]
	s_setprio 0
	s_barrier
	s_cbranch_scc0 .LBB0_2495
	s_and_b64 vcc, exec, s[36:37]
	s_cbranch_vccz .LBB0_2498
	s_barrier
